# v40: v37 + SG loop: delete two false-dependency vmcnt waits (odd half of op_sel-broadcast pairs was a pending prefetch dest) so next-unit prefetch overlaps the unit
# baseline (speedup 1.0000x reference)
; #define LAS __attribute__((address_space(3)))
; __device__ __forceinline__ unsigned pk2(float lo, float hi) { const f32x2 v = {lo, hi}; return __builtin_bit_cast(unsigned, __builtin_convertvector(v, bf16x2_hw)); }
; __device__ __forceinline__ void p3_sg(LAS unsigned char* lds_, const Params& p) {
;     ...
;         { const int tm = F.wave; const f32x4 stA = *(const LAS f32x4*)(F.lds + ST_OFF + (16 * tm + 4 * lq) * 8), stB = *(const LAS f32x4*)(F.lds + ST_OFF + (16 * tm + 4 * lq + 2) * 8);
;           const float mu[4] = {stA[0], stA[2], stB[0], stB[2]}, rs[4] = {stA[1], stA[3], stB[1], stB[3]};
; #pragma unroll
;           for (int ks = 0; ks < 4; ++ks) { const f32x4 z = (f32x4){0.f, 0.f, 0.f, 0.f}; const bf16x8 a = __builtin_bit_cast(bf16x8, R.av[ks]);
;               const f32x4 d0 = __builtin_amdgcn_mfma_f32_16x16x32_bf16(a, Iev, z, 0, 0, 0), d1 = __builtin_amdgcn_mfma_f32_16x16x32_bf16(a, Iod, z, 0, 0, 0);
;               const int ca = 32 * ks + l15, cb = ca + 16; const float ga = R.lg[2 * ks], ba = R.lb[2 * ks], gb = R.lg[2 * ks + 1], bb = R.lb[2 * ks + 1];
;               float ya[4], yb[4];
; #pragma unroll
;               for (int r = 0; r < 4; ++r) { ya[r] = (d0[r] - mu[r]) * rs[r] * ga + ba; yb[r] = (d1[r] - mu[r]) * rs[r] * gb + bb; }
;               *(LAS v2u*)(F.lds + VN_OFF + ca * STR + (16 * tm + 4 * lq) * 2) = (v2u){pk2(ya[0], ya[1]), pk2(ya[2], ya[3])};
;               *(LAS v2u*)(F.lds + VN_OFF + cb * STR + (16 * tm + 4 * lq) * 2) = (v2u){pk2(yb[0], yb[1]), pk2(yb[2], yb[3])}; } }
.LBB0_347:
	s_or_b64 exec, exec, s[16:17]
	s_waitcnt lgkmcnt(0)
	s_barrier
	s_waitcnt lgkmcnt(0)
	ds_read_b128 v[58:61], v103
	ds_read_b128 v[66:69], v103 offset:16
	v_mfma_f32_16x16x32_bf16 v[62:65], v[54:57], v[6:9], 0
	s_lshl_b32 s14, s14, 9
	s_sub_i32 s15, s23, s14
	s_waitcnt lgkmcnt(1)
	v_mov_b32_e32 v70, v58
	v_mfma_f32_16x16x32_bf16 v[54:57], v[54:57], v[2:5], 0
	v_mov_b32_e32 v71, v60
	v_mov_b32_e32 v60, v59
	s_nop 0
	v_pk_add_f32 v[62:63], v[62:63], v[70:71] neg_lo:[0,1] neg_hi:[0,1]
	s_waitcnt lgkmcnt(0)
	v_mov_b32_e32 v72, v66
	v_mov_b32_e32 v73, v68
	s_nop 0
	v_pk_add_f32 v[54:55], v[54:55], v[70:71] neg_lo:[0,1] neg_hi:[0,1]
	v_pk_mul_f32 v[58:59], v[60:61], v[62:63]
	v_pk_mul_f32 v[54:55], v[60:61], v[54:55]
	v_mov_b32_e32 v68, v67
	v_pk_fma_f32 v[62:63], v[154:155], v[54:55], v[158:159] op_sel_hi:[0,1,0]
	v_pk_add_f32 v[54:55], v[64:65], v[72:73] neg_lo:[0,1] neg_hi:[0,1]
	v_pk_add_f32 v[56:57], v[56:57], v[72:73] neg_lo:[0,1] neg_hi:[0,1]
	v_pk_mul_f32 v[54:55], v[68:69], v[54:55]
	v_pk_fma_f32 v[58:59], v[156:157], v[58:59], v[160:161] op_sel_hi:[0,1,0]
	v_pk_fma_f32 v[54:55], v[156:157], v[54:55], v[160:161] op_sel_hi:[0,1,0]
	v_pk_mul_f32 v[56:57], v[68:69], v[56:57]
	s_lshr_b32 s16, s15, 15
	v_pk_fma_f32 v[64:65], v[154:155], v[56:57], v[158:159] op_sel_hi:[0,1,0]
	v_cvt_pk_bf16_f32 v56, v58, v59
	v_cvt_pk_bf16_f32 v57, v54, v55
	ds_write_b64 v105, v[56:57] offset:34816
	v_mfma_f32_16x16x32_bf16 v[54:57], v[50:53], v[6:9], 0
	v_cvt_pk_bf16_f32 v58, v62, v63
	v_cvt_pk_bf16_f32 v59, v64, v65
	ds_write_b64 v105, v[58:59] offset:39168
	v_mfma_f32_16x16x32_bf16 v[50:53], v[50:53], v[2:5], 0
	s_bfe_u32 s17, s16, 0x70009
	s_nop 2
	v_pk_add_f32 v[54:55], v[54:55], v[70:71] neg_lo:[0,1] neg_hi:[0,1]
	s_add_i32 s17, s15, s17
	v_pk_mul_f32 v[54:55], v[60:61], v[54:55]
	s_sext_i32_i16 s19, s17
	v_pk_add_f32 v[50:51], v[50:51], v[70:71] neg_lo:[0,1] neg_hi:[0,1]
	v_pk_add_f32 v[52:53], v[52:53], v[72:73] neg_lo:[0,1] neg_hi:[0,1]
	v_pk_mul_f32 v[50:51], v[60:61], v[50:51]
	v_pk_fma_f32 v[54:55], v[148:149], v[54:55], v[152:153] op_sel_hi:[0,1,0]
	v_pk_fma_f32 v[58:59], v[146:147], v[50:51], v[150:151] op_sel_hi:[0,1,0]
	v_pk_add_f32 v[50:51], v[56:57], v[72:73] neg_lo:[0,1] neg_hi:[0,1]
	v_pk_mul_f32 v[52:53], v[68:69], v[52:53]
	v_pk_mul_f32 v[50:51], v[68:69], v[50:51]
	v_pk_fma_f32 v[56:57], v[146:147], v[52:53], v[150:151] op_sel_hi:[0,1,0]
	v_pk_fma_f32 v[50:51], v[148:149], v[50:51], v[152:153] op_sel_hi:[0,1,0]
	v_cvt_pk_bf16_f32 v52, v54, v55
	v_cvt_pk_bf16_f32 v53, v50, v51
	ds_write_b64 v105, v[52:53] offset:43520
	v_mfma_f32_16x16x32_bf16 v[50:53], v[46:49], v[6:9], 0
	v_cvt_pk_bf16_f32 v54, v58, v59
	v_cvt_pk_bf16_f32 v55, v56, v57
	ds_write_b64 v105, v[54:55] offset:47872
	v_mfma_f32_16x16x32_bf16 v[46:49], v[46:49], v[2:5], 0
	s_and_b32 s17, s17, 0xff80
	s_nop 2
	v_pk_add_f32 v[50:51], v[50:51], v[70:71] neg_lo:[0,1] neg_hi:[0,1]
	s_sub_i32 s17, s15, s17
	v_pk_mul_f32 v[50:51], v[60:61], v[50:51]
	s_bfe_i32 s20, s17, 0x80000
	v_pk_add_f32 v[46:47], v[46:47], v[70:71] neg_lo:[0,1] neg_hi:[0,1]
	v_pk_add_f32 v[48:49], v[48:49], v[72:73] neg_lo:[0,1] neg_hi:[0,1]
	v_pk_mul_f32 v[46:47], v[60:61], v[46:47]
	v_pk_fma_f32 v[50:51], v[142:143], v[50:51], v[144:145] op_sel_hi:[0,1,0]
	v_pk_fma_f32 v[54:55], v[138:139], v[46:47], v[140:141] op_sel_hi:[0,1,0]
	v_pk_add_f32 v[46:47], v[52:53], v[72:73] neg_lo:[0,1] neg_hi:[0,1]
	v_pk_mul_f32 v[48:49], v[68:69], v[48:49]
	v_pk_mul_f32 v[46:47], v[68:69], v[46:47]
	v_pk_fma_f32 v[52:53], v[138:139], v[48:49], v[140:141] op_sel_hi:[0,1,0]
	v_pk_fma_f32 v[46:47], v[142:143], v[46:47], v[144:145] op_sel_hi:[0,1,0]
	v_cvt_pk_bf16_f32 v48, v50, v51
	v_cvt_pk_bf16_f32 v49, v46, v47
	ds_write_b64 v105, v[48:49] offset:52224
	v_mfma_f32_16x16x32_bf16 v[46:49], v[42:45], v[6:9], 0
	v_cvt_pk_bf16_f32 v50, v54, v55
	v_cvt_pk_bf16_f32 v51, v52, v53
	ds_write_b64 v105, v[50:51] offset:56576
	v_mfma_f32_16x16x32_bf16 v[42:45], v[42:45], v[2:5], 0
	s_bfe_u32 s20, s20, 0x2000d
	s_nop 2
	v_pk_add_f32 v[46:47], v[46:47], v[70:71] neg_lo:[0,1] neg_hi:[0,1]
	v_pk_add_f32 v[48:49], v[48:49], v[72:73] neg_lo:[0,1] neg_hi:[0,1]
	v_pk_mul_f32 v[46:47], v[60:61], v[46:47]
	v_pk_mul_f32 v[48:49], v[68:69], v[48:49]
	v_pk_add_f32 v[42:43], v[42:43], v[70:71] neg_lo:[0,1] neg_hi:[0,1]
	v_pk_add_f32 v[44:45], v[44:45], v[72:73] neg_lo:[0,1] neg_hi:[0,1]
	v_pk_mul_f32 v[42:43], v[60:61], v[42:43]
	v_pk_mul_f32 v[44:45], v[68:69], v[44:45]
	v_pk_fma_f32 v[46:47], v[134:135], v[46:47], v[136:137] op_sel_hi:[0,1,0]
	v_pk_fma_f32 v[42:43], v[130:131], v[42:43], v[132:133] op_sel_hi:[0,1,0]
	v_pk_fma_f32 v[48:49], v[134:135], v[48:49], v[136:137] op_sel_hi:[0,1,0]
	v_pk_fma_f32 v[44:45], v[130:131], v[44:45], v[132:133] op_sel_hi:[0,1,0]
	v_cvt_pk_bf16_f32 v46, v46, v47
	v_cvt_pk_bf16_f32 v47, v48, v49
	v_cvt_pk_bf16_f32 v42, v42, v43
	v_cvt_pk_bf16_f32 v43, v44, v45
	ds_write_b64 v105, v[46:47] offset:60928
	ds_write_b64 v105, v[42:43] offset:65280
	s_waitcnt lgkmcnt(0)
	s_barrier
; __device__ __forceinline__ void p3_sg(LAS unsigned char* lds_, const Params& p) {
;     ...
;         f32x4 acc[8];
; #pragma unroll
;         for (int ti = 0; ti < 8; ++ti) acc[ti] = (f32x4){0.f, 0.f, 0.f, 0.f};
; #pragma unroll
;         for (int ks = 0; ks < 4; ++ks) { const bf16x8 a = ldfrag(F.lds + VN_OFF, 16 * F.wave + l15, STR, (8 * lq + 32 * ks) * 2);
; #pragma unroll
;             for (int ti = 0; ti < 8; ++ti) { const bf16x8 bb = ldfrag(F.lds + WS_OFF, 16 * ti + l15, STR, (8 * lq + 32 * ks) * 2); acc[ti] = __builtin_amdgcn_mfma_f32_16x16x32_bf16(a, bb, acc[ti], 0, 0, 0); } }
	ds_read_b128 v[42:45], v107 offset:34816
	ds_read_b128 v[46:49], v109
	ds_read_b128 v[50:53], v107 offset:34880
	ds_read_b128 v[54:57], v109 offset:64
	ds_read_b128 v[58:61], v109 offset:4352
	ds_read_b128 v[62:65], v109 offset:4416
	ds_read_b128 v[66:69], v109 offset:8704
	ds_read_b128 v[70:73], v109 offset:8768
	ds_read_b128 v[164:167], v109 offset:13056
	ds_read_b128 v[168:171], v109 offset:13120
	s_waitcnt lgkmcnt(8)
	v_mfma_f32_16x16x32_bf16 v[46:49], v[42:45], v[46:49], 0
	ds_read_b128 v[172:175], v109 offset:17408
	ds_read_b128 v[176:179], v109 offset:17472
	ds_read_b128 v[180:183], v109 offset:21760
	ds_read_b128 v[184:187], v109 offset:21824
	ds_read_b128 v[188:191], v109 offset:26112
	ds_read_b128 v[192:195], v109 offset:26176
	s_waitcnt lgkmcnt(11)
	v_mfma_f32_16x16x32_bf16 v[58:61], v[42:45], v[58:61], 0
	ds_read_b128 v[196:199], v109 offset:30464
	ds_read_b128 v[200:203], v109 offset:30528
	s_bfe_u32 s16, s16, 0x2000e
	s_add_i32 s17, s17, s20
	s_waitcnt lgkmcnt(9)
	v_mfma_f32_16x16x32_bf16 v[164:167], v[42:45], v[164:167], 0
	s_add_i32 s16, s15, s16
	s_sext_i32_i8 s17, s17
	s_and_b32 s16, s16, 0xfffc
	v_mfma_f32_16x16x32_bf16 v[46:49], v[50:53], v[54:57], v[46:49]
	s_sub_i32 s15, s15, s16
	s_lshl_b32 s16, s19, 5
	s_lshl_b32 s17, s17, 5
	v_mfma_f32_16x16x32_bf16 v[54:57], v[50:53], v[62:65], v[58:61]
	s_and_b32 s16, s16, 0xfffff000
	s_and_b32 s17, s17, 0xffffff80
	s_sext_i32_i16 s15, s15
	s_waitcnt lgkmcnt(8)
	v_mfma_f32_16x16x32_bf16 v[62:65], v[50:53], v[168:171], v[164:167]
	ds_read_b128 v[168:171], v107 offset:34944
	s_add_i32 s17, s17, s16
	s_lshl_b32 s15, s15, 7
	v_mfma_f32_16x16x32_bf16 v[66:69], v[42:45], v[66:69], 0
	s_add_i32 s14, s15, s14
	s_ashr_i32 s15, s14, 31
	s_lshl_b64 s[14:15], s[14:15], 1
	s_waitcnt lgkmcnt(8)
	v_mfma_f32_16x16x32_bf16 v[172:175], v[42:45], v[172:175], 0
	s_andn2_b64 vcc, exec, s[12:13]
	s_waitcnt vmcnt(0)
	v_mov_b32_e32 v132, v162
	v_mov_b32_e32 v136, v161
	s_waitcnt lgkmcnt(6)
	v_mfma_f32_16x16x32_bf16 v[180:183], v[42:45], v[180:183], 0
	v_mov_b32_e32 v140, v159
	v_mov_b32_e32 v144, v157
	v_mov_b32_e32 v150, v155
	s_waitcnt lgkmcnt(4)
	v_mfma_f32_16x16x32_bf16 v[188:191], v[42:45], v[188:191], 0
	v_mov_b32_e32 v152, v153
	v_mov_b32_e32 v158, v151
	v_mov_b32_e32 v160, v149
	s_waitcnt lgkmcnt(2)
	v_mfma_f32_16x16x32_bf16 v[42:45], v[42:45], v[196:199], 0
	v_mov_b32_e32 v130, v147
	v_mov_b32_e32 v134, v145
	v_mov_b32_e32 v138, v143
	v_mfma_f32_16x16x32_bf16 v[58:61], v[50:53], v[70:73], v[66:69]
	v_mov_b32_e32 v142, v141
	v_mov_b32_e32 v146, v139
	v_mov_b32_e32 v148, v137
	v_mfma_f32_16x16x32_bf16 v[66:69], v[50:53], v[176:179], v[172:175]
	v_mov_b32_e32 v154, v135
	v_mov_b32_e32 v156, v133
	s_mov_b32 s23, s25
	v_mfma_f32_16x16x32_bf16 v[70:73], v[50:53], v[184:187], v[180:183]
	v_mfma_f32_16x16x32_bf16 v[164:167], v[50:53], v[192:195], v[188:191]
	s_waitcnt lgkmcnt(1)
	v_mfma_f32_16x16x32_bf16 v[42:45], v[50:53], v[200:203], v[42:45]
	ds_read_b128 v[50:53], v109 offset:128
	ds_read_b128 v[172:175], v107 offset:35008
	ds_read_b128 v[176:179], v109 offset:192
	s_waitcnt lgkmcnt(2)
	v_mfma_f32_16x16x32_bf16 v[46:49], v[168:171], v[50:53], v[46:49]
	ds_read_b128 v[50:53], v109 offset:4480
	ds_read_b128 v[180:183], v109 offset:4544
	s_waitcnt lgkmcnt(1)
	v_mfma_f32_16x16x32_bf16 v[50:53], v[168:171], v[50:53], v[54:57]
	s_nop 2
	ds_read_b128 v[54:57], v109 offset:8832
	ds_read_b128 v[184:187], v109 offset:8896
	s_waitcnt lgkmcnt(1)
	v_mfma_f32_16x16x32_bf16 v[54:57], v[168:171], v[54:57], v[58:61]
	s_nop 2
	ds_read_b128 v[58:61], v109 offset:13184
	ds_read_b128 v[188:191], v109 offset:13248
	s_waitcnt lgkmcnt(1)
	v_mfma_f32_16x16x32_bf16 v[58:61], v[168:171], v[58:61], v[62:65]
	s_nop 2
	ds_read_b128 v[62:65], v109 offset:17536
	ds_read_b128 v[192:195], v109 offset:17600
	s_waitcnt lgkmcnt(1)
	v_mfma_f32_16x16x32_bf16 v[62:65], v[168:171], v[62:65], v[66:69]
	s_nop 2
	ds_read_b128 v[66:69], v109 offset:21888
	ds_read_b128 v[196:199], v109 offset:21952
	s_waitcnt lgkmcnt(1)
	v_mfma_f32_16x16x32_bf16 v[66:69], v[168:171], v[66:69], v[70:73]
	s_nop 2
	ds_read_b128 v[70:73], v109 offset:26240
	ds_read_b128 v[200:203], v109 offset:26304
	s_waitcnt lgkmcnt(1)
	v_mfma_f32_16x16x32_bf16 v[70:73], v[168:171], v[70:73], v[164:167]
	s_nop 2
	ds_read_b128 v[164:167], v109 offset:30592
	ds_read_b128 v[204:207], v109 offset:30656
	v_mfma_f32_16x16x32_bf16 v[46:49], v[172:175], v[176:179], v[46:49]
	s_waitcnt lgkmcnt(1)
; __device__ __forceinline__ unsigned pk2(float lo, float hi) { const f32x2 v = {lo, hi}; return __builtin_bit_cast(unsigned, __builtin_convertvector(v, bf16x2_hw)); }
; __device__ __forceinline__ void st_global_b64(void* p, v2u v) { asm volatile("global_store_dwordx2 %0, %1, off\n\ts_nop 1" :: "v"(p), "v"(v) : "memory"); }
; __device__ __forceinline__ void p3_sg(LAS unsigned char* lds_, const Params& p) {
;     ...
;         for (int ks = 0; ks < 4; ++ks) { const bf16x8 a = ldfrag(F.lds + VN_OFF, 16 * F.wave + l15, STR, (8 * lq + 32 * ks) * 2);
; #pragma unroll
;             for (int ti = 0; ti < 8; ++ti) { const bf16x8 bb = ldfrag(F.lds + WS_OFF, 16 * ti + l15, STR, (8 * lq + 32 * ks) * 2); acc[ti] = __builtin_amdgcn_mfma_f32_16x16x32_bf16(a, bb, acc[ti], 0, 0, 0); } }
; #pragma unroll
;         for (int ti = 0; ti < 8; ++ti) { const int i = 16 * ti + l15, c = 16 * F.wave + 4 * lq; const float bs = bsv[ti];
;             const v2u uu = R.uu[ti];
;             const float o0 = bf_lo(uu.x) * (acc[ti][0] + bs), o1 = bf_hi(uu.x) * (acc[ti][1] + bs), o2 = bf_lo(uu.y) * (acc[ti][2] + bs), o3 = bf_hi(uu.y) * (acc[ti][3] + bs);
;             v2u w; w.x = pk2(o0, o1); w.y = pk2(o2, o3); st_global_b64(Y + (size_t)(row0 + i) * D + VALW + ch0 + c, w); }
	v_mfma_f32_16x16x32_bf16 v[42:45], v[168:171], v[164:167], v[42:45]
	v_or_b32_e32 v164, s17, v95
	v_lshlrev_b32_e32 v166, 16, v112
	v_and_b32_e32 v167, 0xffff0000, v112
	s_nop 2
	v_pk_add_f32 v[46:47], v[94:95], v[46:47] op_sel_hi:[0,1]
	v_lshlrev_b32_e32 v112, 16, v113
	v_and_b32_e32 v113, 0xffff0000, v113
	v_pk_add_f32 v[48:49], v[94:95], v[48:49] op_sel_hi:[0,1]
	v_pk_mul_f32 v[46:47], v[46:47], v[166:167]
	v_pk_mul_f32 v[48:49], v[48:49], v[112:113]
	v_ashrrev_i32_e32 v165, 31, v164
	v_cvt_pk_bf16_f32 v46, v46, v47
	v_cvt_pk_bf16_f32 v47, v48, v49
	v_lshlrev_b64 v[48:49], 13, v[164:165]
	v_mfma_f32_16x16x32_bf16 v[50:53], v[172:175], v[180:183], v[50:53]
	v_lshl_add_u64 v[48:49], s[96:97], 0, v[48:49]
	v_lshl_add_u64 v[48:49], v[48:49], 0, s[14:15]
	v_lshl_add_u64 v[48:49], v[48:49], 0, v[86:87]
	v_lshl_add_u64 v[48:49], v[48:49], 0, s[10:11]
	global_store_dwordx2 v[48:49], v[46:47], off
	s_nop 1
	v_lshlrev_b32_e32 v46, 16, v110
	v_and_b32_e32 v47, 0xffff0000, v110
	s_nop 1
	v_pk_add_f32 v[48:49], v[96:97], v[50:51] op_sel_hi:[0,1]
	v_pk_mul_f32 v[46:47], v[48:49], v[46:47]
	v_lshlrev_b32_e32 v48, 16, v111
	v_and_b32_e32 v49, 0xffff0000, v111
	v_pk_add_f32 v[50:51], v[96:97], v[52:53] op_sel_hi:[0,1]
	v_pk_mul_f32 v[48:49], v[50:51], v[48:49]
	v_cvt_pk_bf16_f32 v46, v46, v47
	v_cvt_pk_bf16_f32 v47, v48, v49
	v_or_b32_e32 v48, 16, v164
	v_ashrrev_i32_e32 v49, 31, v48
	v_lshlrev_b64 v[48:49], 13, v[48:49]
	v_mfma_f32_16x16x32_bf16 v[54:57], v[172:175], v[184:187], v[54:57]
	v_lshl_add_u64 v[48:49], s[96:97], 0, v[48:49]
	v_lshl_add_u64 v[48:49], v[48:49], 0, s[14:15]
	v_lshl_add_u64 v[48:49], v[48:49], 0, v[86:87]
	v_lshl_add_u64 v[48:49], v[48:49], 0, s[10:11]
	global_store_dwordx2 v[48:49], v[46:47], off
	s_nop 1
	v_lshlrev_b32_e32 v46, 16, v92
	v_and_b32_e32 v47, 0xffff0000, v92
	s_nop 1
	v_pk_add_f32 v[48:49], v[98:99], v[54:55] op_sel_hi:[0,1]
	v_pk_mul_f32 v[46:47], v[48:49], v[46:47]
	v_lshlrev_b32_e32 v48, 16, v93
	v_and_b32_e32 v49, 0xffff0000, v93
	v_pk_add_f32 v[50:51], v[98:99], v[56:57] op_sel_hi:[0,1]
	v_pk_mul_f32 v[48:49], v[50:51], v[48:49]
	v_cvt_pk_bf16_f32 v46, v46, v47
	v_cvt_pk_bf16_f32 v47, v48, v49
	v_or_b32_e32 v48, 32, v164
	v_ashrrev_i32_e32 v49, 31, v48
	v_lshlrev_b64 v[48:49], 13, v[48:49]
	v_mfma_f32_16x16x32_bf16 v[58:61], v[172:175], v[188:191], v[58:61]
	v_lshl_add_u64 v[48:49], s[96:97], 0, v[48:49]
	v_lshl_add_u64 v[48:49], v[48:49], 0, s[14:15]
	v_lshl_add_u64 v[48:49], v[48:49], 0, v[86:87]
	v_lshl_add_u64 v[48:49], v[48:49], 0, s[10:11]
	global_store_dwordx2 v[48:49], v[46:47], off
	s_nop 1
	v_lshlrev_b32_e32 v46, 16, v90
	v_and_b32_e32 v47, 0xffff0000, v90
	s_nop 1
	v_pk_add_f32 v[48:49], v[100:101], v[58:59] op_sel_hi:[0,1]
	v_pk_mul_f32 v[46:47], v[48:49], v[46:47]
	v_lshlrev_b32_e32 v48, 16, v91
	v_and_b32_e32 v49, 0xffff0000, v91
	v_pk_add_f32 v[50:51], v[100:101], v[60:61] op_sel_hi:[0,1]
	v_pk_mul_f32 v[48:49], v[50:51], v[48:49]
	v_cvt_pk_bf16_f32 v46, v46, v47
	v_cvt_pk_bf16_f32 v47, v48, v49
	v_or_b32_e32 v48, 48, v164
	v_ashrrev_i32_e32 v49, 31, v48
	v_lshlrev_b64 v[48:49], 13, v[48:49]
	v_mfma_f32_16x16x32_bf16 v[62:65], v[172:175], v[192:195], v[62:65]
	v_lshl_add_u64 v[48:49], s[96:97], 0, v[48:49]
	v_lshl_add_u64 v[48:49], v[48:49], 0, s[14:15]
	v_lshl_add_u64 v[48:49], v[48:49], 0, v[86:87]
	v_lshl_add_u64 v[48:49], v[48:49], 0, s[10:11]
	global_store_dwordx2 v[48:49], v[46:47], off
	s_nop 1
	v_lshlrev_b32_e32 v46, 16, v88
	v_and_b32_e32 v47, 0xffff0000, v88
	s_nop 1
	v_pk_add_f32 v[48:49], v[102:103], v[62:63] op_sel_hi:[0,1]
	v_pk_mul_f32 v[46:47], v[48:49], v[46:47]
	v_lshlrev_b32_e32 v48, 16, v89
	v_and_b32_e32 v49, 0xffff0000, v89
	v_pk_add_f32 v[50:51], v[102:103], v[64:65] op_sel_hi:[0,1]
	v_pk_mul_f32 v[48:49], v[50:51], v[48:49]
	v_cvt_pk_bf16_f32 v46, v46, v47
	v_cvt_pk_bf16_f32 v47, v48, v49
	v_or_b32_e32 v48, 64, v164
	v_ashrrev_i32_e32 v49, 31, v48
	v_lshlrev_b64 v[48:49], 13, v[48:49]
	v_mfma_f32_16x16x32_bf16 v[66:69], v[172:175], v[196:199], v[66:69]
	v_lshl_add_u64 v[48:49], s[96:97], 0, v[48:49]
	v_lshl_add_u64 v[48:49], v[48:49], 0, s[14:15]
	v_lshl_add_u64 v[48:49], v[48:49], 0, v[86:87]
	v_lshl_add_u64 v[48:49], v[48:49], 0, s[10:11]
	global_store_dwordx2 v[48:49], v[46:47], off
	s_nop 1
	v_lshlrev_b32_e32 v46, 16, v84
	v_and_b32_e32 v47, 0xffff0000, v84
	s_nop 1
	v_pk_add_f32 v[48:49], v[104:105], v[66:67] op_sel_hi:[0,1]
	v_pk_mul_f32 v[46:47], v[48:49], v[46:47]
	v_lshlrev_b32_e32 v48, 16, v85
	v_and_b32_e32 v49, 0xffff0000, v85
	v_pk_add_f32 v[50:51], v[104:105], v[68:69] op_sel_hi:[0,1]
	v_pk_mul_f32 v[48:49], v[50:51], v[48:49]
	v_cvt_pk_bf16_f32 v46, v46, v47
	v_cvt_pk_bf16_f32 v47, v48, v49
	v_or_b32_e32 v48, 0x50, v164
	v_ashrrev_i32_e32 v49, 31, v48
	v_lshlrev_b64 v[48:49], 13, v[48:49]
	v_mfma_f32_16x16x32_bf16 v[70:73], v[172:175], v[200:203], v[70:73]
	v_lshl_add_u64 v[48:49], s[96:97], 0, v[48:49]
	v_lshl_add_u64 v[48:49], v[48:49], 0, s[14:15]
	v_lshl_add_u64 v[48:49], v[48:49], 0, v[86:87]
	v_lshl_add_u64 v[48:49], v[48:49], 0, s[10:11]
	global_store_dwordx2 v[48:49], v[46:47], off
	s_nop 1
	v_lshlrev_b32_e32 v46, 16, v78
	v_and_b32_e32 v47, 0xffff0000, v78
	s_nop 1
	v_pk_add_f32 v[48:49], v[106:107], v[70:71] op_sel_hi:[0,1]
	v_pk_mul_f32 v[46:47], v[48:49], v[46:47]
	v_lshlrev_b32_e32 v48, 16, v79
	v_and_b32_e32 v49, 0xffff0000, v79
	v_pk_add_f32 v[50:51], v[106:107], v[72:73] op_sel_hi:[0,1]
	v_pk_mul_f32 v[48:49], v[50:51], v[48:49]
	v_cvt_pk_bf16_f32 v46, v46, v47
	v_cvt_pk_bf16_f32 v47, v48, v49
	v_or_b32_e32 v48, 0x60, v164
	v_ashrrev_i32_e32 v49, 31, v48
	s_waitcnt lgkmcnt(0)
; __device__ __forceinline__ unsigned pk2(float lo, float hi) { const f32x2 v = {lo, hi}; return __builtin_bit_cast(unsigned, __builtin_convertvector(v, bf16x2_hw)); }
; __device__ __forceinline__ void st_global_b64(void* p, v2u v) { asm volatile("global_store_dwordx2 %0, %1, off\n\ts_nop 1" :: "v"(p), "v"(v) : "memory"); }
; __device__ __forceinline__ void p3_sg(LAS unsigned char* lds_, const Params& p) {
;     ...
;         SG_DECODE(un) const int g = g_, row0 = row0_, ch0 = ch0_;
;         R = Rn;
;         if (un + 1 < u1) SG_LOAD(Rn, un + 1);
;     ...
;         for (int ti = 0; ti < 8; ++ti) { const int i = 16 * ti + l15, c = 16 * F.wave + 4 * lq; const float bs = bsv[ti];
;             const v2u uu = R.uu[ti];
;             const float o0 = bf_lo(uu.x) * (acc[ti][0] + bs), o1 = bf_hi(uu.x) * (acc[ti][1] + bs), o2 = bf_lo(uu.y) * (acc[ti][2] + bs), o3 = bf_hi(uu.y) * (acc[ti][3] + bs);
;             v2u w; w.x = pk2(o0, o1); w.y = pk2(o2, o3); st_global_b64(Y + (size_t)(row0 + i) * D + VALW + ch0 + c, w); }
	v_mfma_f32_16x16x32_bf16 v[42:45], v[172:175], v[204:207], v[42:45]
	v_lshlrev_b64 v[48:49], 13, v[48:49]
	v_lshl_add_u64 v[48:49], s[96:97], 0, v[48:49]
	v_lshl_add_u64 v[48:49], v[48:49], 0, s[14:15]
	v_lshl_add_u64 v[48:49], v[48:49], 0, v[86:87]
	v_lshl_add_u64 v[48:49], v[48:49], 0, s[10:11]
	global_store_dwordx2 v[48:49], v[46:47], off
	s_nop 1
	v_lshlrev_b32_e32 v46, 16, v76
	v_and_b32_e32 v47, 0xffff0000, v76
	s_nop 0
	v_pk_add_f32 v[42:43], v[108:109], v[42:43] op_sel_hi:[0,1]
	v_pk_mul_f32 v[42:43], v[42:43], v[46:47]
	v_lshlrev_b32_e32 v46, 16, v77
	v_and_b32_e32 v47, 0xffff0000, v77
	v_pk_add_f32 v[44:45], v[108:109], v[44:45] op_sel_hi:[0,1]
	v_pk_mul_f32 v[44:45], v[44:45], v[46:47]
	v_cvt_pk_bf16_f32 v42, v42, v43
	v_cvt_pk_bf16_f32 v43, v44, v45
	v_or_b32_e32 v44, 0x70, v164
	v_ashrrev_i32_e32 v45, 31, v44
	v_lshlrev_b64 v[44:45], 13, v[44:45]
	v_lshl_add_u64 v[44:45], s[96:97], 0, v[44:45]
	v_lshl_add_u64 v[44:45], v[44:45], 0, s[14:15]
	v_lshl_add_u64 v[44:45], v[44:45], 0, v[86:87]
	v_lshl_add_u64 v[44:45], v[44:45], 0, s[10:11]
	global_store_dwordx2 v[44:45], v[42:43], off
	s_nop 1
	v_mov_b64_e32 v[60:61], v[28:29]
	v_mov_b64_e32 v[64:65], v[32:33]
	v_mov_b64_e32 v[68:69], v[36:37]
	v_mov_b64_e32 v[72:73], v[40:41]
	v_mov_b64_e32 v[44:45], v[12:13]
	v_mov_b64_e32 v[48:49], v[16:17]
	v_mov_b64_e32 v[52:53], v[20:21]
	v_mov_b64_e32 v[56:57], v[24:25]
	v_mov_b64_e32 v[76:77], v[122:123]
	v_mov_b64_e32 v[78:79], v[124:125]
	v_mov_b64_e32 v[84:85], v[126:127]
	v_mov_b64_e32 v[88:89], v[128:129]
	v_mov_b64_e32 v[90:91], v[114:115]
	v_mov_b64_e32 v[92:93], v[116:117]
	v_mov_b64_e32 v[110:111], v[118:119]
	v_mov_b64_e32 v[112:113], v[120:121]
	v_mov_b64_e32 v[58:59], v[26:27]
	v_mov_b64_e32 v[62:63], v[30:31]
	v_mov_b64_e32 v[66:67], v[34:35]
	v_mov_b64_e32 v[70:71], v[38:39]
	v_mov_b64_e32 v[42:43], v[10:11]
	v_mov_b64_e32 v[46:47], v[14:15]
	v_mov_b64_e32 v[50:51], v[18:19]
	v_mov_b64_e32 v[54:55], v[22:23]
	s_cbranch_vccz .LBB0_357
